# v21 + unit-seam store-drain removal: attention unit seams wait lgkmcnt only before the LDS-reuse barrier, stores drain under the next prologue; vmcnt(0) kept at phase-D exit
# speedup vs baseline: 1.0045x; 1.0045x over previous
.LBB0_528:
	s_or_b64 exec, exec, s[8:9]
	s_add_i32 s39, s39, s30
	s_cmpk_gt_i32 s39, 0xff
	s_waitcnt lgkmcnt(0)
	s_barrier
	s_cbranch_scc1 .LBB0_615

.LBB0_571:
	s_or_b64 exec, exec, s[8:9]
	v_mov_b32_e32 v0, v1
	s_waitcnt lgkmcnt(0)
	s_barrier
	s_lshl_b32 s8, s43, 8
	v_mbcnt_lo_u32_b32 v0, -1, v0
	v_mbcnt_hi_u32_b32 v0, -1, v0
	v_add_u32_e32 v98, s54, v0
	v_mov_b64_e32 v[2:3], s[70:71]
	v_readfirstlane_b32 s9, v98
	s_ashr_i32 s0, s9, 6
	s_lshl_b32 s6, s0, 5
	v_and_b32_e32 v238, 31, v98
	s_add_i32 s20, s6, s8
	v_or_b32_e32 v34, s20, v238
	v_bfe_u32 v237, v98, 5, 1
	v_mad_i64_i32 v[2:3], s[10:11], v34, s46, v[2:3]
	s_lshl_b32 s86, s45, 1
	v_lshl_add_u64 v[2:3], v[2:3], 0, s[86:87]
	v_lshlrev_b32_e32 v0, 4, v237
	v_lshl_add_u64 v[2:3], v[2:3], 0, v[0:1]
	global_load_dwordx4 v[38:41], v[2:3], off
	global_load_dwordx4 v[46:49], v[2:3], off offset:32
	global_load_dwordx4 v[54:57], v[2:3], off offset:64
	global_load_dwordx4 v[62:65], v[2:3], off offset:96
	global_load_dwordx4 v[30:33], v[2:3], off offset:128
	global_load_dwordx4 v[26:29], v[2:3], off offset:160
	global_load_dwordx4 v[22:25], v[2:3], off offset:192
	global_load_dwordx4 v[18:21], v[2:3], off offset:224
	global_load_dwordx4 v[14:17], v[2:3], off offset:256
	global_load_dwordx4 v[6:9], v[2:3], off offset:288
	global_load_dwordx4 v[10:13], v[2:3], off offset:320
	s_nop 0
	global_load_dwordx4 v[2:5], v[2:3], off offset:352
	v_ashrrev_i32_e32 v35, 31, v34
	v_lshl_add_u64 v[34:35], v[34:35], 2, s[68:69]
	global_load_dword v239, v[34:35], off
	s_lshl_b32 s7, s0, 2
	v_bfe_u32 v102, v98, 3, 1
	v_mov_b64_e32 v[100:101], s[66:67]
	s_lshl_b32 s0, s0, 10
	s_add_i32 s0, s0, 0
	s_mov_b32 m0, s0
	s_waitcnt vmcnt(12)
	v_lshlrev_b32_e32 v118, 16, v38
	v_and_b32_e32 v119, 0xffff0000, v38
	v_lshlrev_b32_e32 v120, 16, v39
	v_and_b32_e32 v121, 0xffff0000, v39
	v_pk_mul_f32 v[34:35], v[118:119], v[118:119]
	v_pk_mul_f32 v[36:37], v[120:121], v[120:121]
	v_lshlrev_b32_e32 v122, 16, v40
	v_and_b32_e32 v123, 0xffff0000, v40
	v_pk_mul_f32 v[38:39], v[122:123], v[122:123]
	v_lshlrev_b32_e32 v124, 16, v41
	v_and_b32_e32 v125, 0xffff0000, v41
	v_add_f32_e32 v36, v36, v37
	v_add_f32_e32 v34, v34, v35
	v_pk_mul_f32 v[40:41], v[124:125], v[124:125]
	s_waitcnt vmcnt(11)
	v_lshlrev_b32_e32 v114, 16, v46
	v_and_b32_e32 v115, 0xffff0000, v46
	v_add_f32_e32 v34, v34, v36
	v_add_f32_e32 v35, v38, v39
	v_pk_mul_f32 v[42:43], v[114:115], v[114:115]
	v_lshlrev_b32_e32 v116, 16, v47
	v_and_b32_e32 v117, 0xffff0000, v47
	v_add_f32_e32 v0, v40, v41
	v_add_f32_e32 v34, v35, v34
	v_pk_mul_f32 v[44:45], v[116:117], v[116:117]
	v_lshlrev_b32_e32 v126, 16, v48
	v_and_b32_e32 v127, 0xffff0000, v48
	v_add_f32_e32 v0, v0, v34
	v_add_f32_e32 v34, v42, v43
	v_pk_mul_f32 v[46:47], v[126:127], v[126:127]
	v_lshlrev_b32_e32 v128, 16, v49
	v_and_b32_e32 v129, 0xffff0000, v49
	v_add_f32_e32 v0, v34, v0
	v_add_f32_e32 v34, v44, v45
	v_pk_mul_f32 v[48:49], v[128:129], v[128:129]
	s_waitcnt vmcnt(10)
	v_lshlrev_b32_e32 v130, 16, v54
	v_and_b32_e32 v131, 0xffff0000, v54
	v_add_f32_e32 v0, v34, v0
	v_add_f32_e32 v34, v46, v47
	v_pk_mul_f32 v[50:51], v[130:131], v[130:131]
	v_lshlrev_b32_e32 v132, 16, v55
	v_and_b32_e32 v133, 0xffff0000, v55
	v_add_f32_e32 v0, v34, v0
	v_add_f32_e32 v34, v48, v49
	v_pk_mul_f32 v[52:53], v[132:133], v[132:133]
	v_lshlrev_b32_e32 v134, 16, v56
	v_and_b32_e32 v135, 0xffff0000, v56
	v_add_f32_e32 v0, v34, v0
	v_add_f32_e32 v34, v50, v51
	v_pk_mul_f32 v[54:55], v[134:135], v[134:135]
	v_lshlrev_b32_e32 v136, 16, v57
	v_and_b32_e32 v137, 0xffff0000, v57
	v_add_f32_e32 v0, v34, v0
	v_add_f32_e32 v34, v52, v53
	v_pk_mul_f32 v[56:57], v[136:137], v[136:137]
	s_waitcnt vmcnt(9)
	v_lshlrev_b32_e32 v138, 16, v62
	v_and_b32_e32 v139, 0xffff0000, v62
	v_add_f32_e32 v0, v34, v0
	v_add_f32_e32 v34, v54, v55
	v_pk_mul_f32 v[58:59], v[138:139], v[138:139]
	v_lshlrev_b32_e32 v140, 16, v63
	v_and_b32_e32 v141, 0xffff0000, v63
	v_add_f32_e32 v0, v34, v0
	v_add_f32_e32 v34, v56, v57
	v_pk_mul_f32 v[60:61], v[140:141], v[140:141]
	v_lshlrev_b32_e32 v142, 16, v64
	v_and_b32_e32 v143, 0xffff0000, v64
	v_add_f32_e32 v0, v34, v0
	v_add_f32_e32 v34, v58, v59
	v_pk_mul_f32 v[62:63], v[142:143], v[142:143]
	v_lshlrev_b32_e32 v144, 16, v65
	v_and_b32_e32 v145, 0xffff0000, v65
	v_add_f32_e32 v0, v34, v0
	v_add_f32_e32 v34, v60, v61
	v_pk_mul_f32 v[64:65], v[144:145], v[144:145]
	s_waitcnt vmcnt(8)
	v_lshlrev_b32_e32 v146, 16, v30
	v_and_b32_e32 v147, 0xffff0000, v30
	v_add_f32_e32 v0, v34, v0
	v_add_f32_e32 v34, v62, v63
	v_pk_mul_f32 v[66:67], v[146:147], v[146:147]
	v_lshlrev_b32_e32 v148, 16, v31
	v_and_b32_e32 v149, 0xffff0000, v31
	v_add_f32_e32 v0, v34, v0
	v_add_f32_e32 v34, v64, v65
	v_pk_mul_f32 v[30:31], v[148:149], v[148:149]
	v_lshlrev_b32_e32 v150, 16, v32
	v_and_b32_e32 v151, 0xffff0000, v32
	v_add_f32_e32 v0, v34, v0
	v_add_f32_e32 v34, v66, v67
	v_pk_mul_f32 v[68:69], v[150:151], v[150:151]
	v_lshlrev_b32_e32 v152, 16, v33
	v_and_b32_e32 v153, 0xffff0000, v33
	v_add_f32_e32 v0, v34, v0
	v_add_f32_e32 v30, v30, v31
	v_pk_mul_f32 v[32:33], v[152:153], v[152:153]
	s_waitcnt vmcnt(7)
	v_lshlrev_b32_e32 v154, 16, v26
	v_and_b32_e32 v155, 0xffff0000, v26
	v_add_f32_e32 v0, v30, v0
	v_add_f32_e32 v30, v68, v69
	v_pk_mul_f32 v[70:71], v[154:155], v[154:155]
	v_lshlrev_b32_e32 v160, 16, v27
	v_and_b32_e32 v161, 0xffff0000, v27
	v_add_f32_e32 v0, v30, v0
	v_add_f32_e32 v30, v32, v33
	v_pk_mul_f32 v[26:27], v[160:161], v[160:161]
	v_lshlrev_b32_e32 v158, 16, v28
	v_and_b32_e32 v159, 0xffff0000, v28
	v_add_f32_e32 v0, v30, v0
	v_add_f32_e32 v30, v70, v71
	v_pk_mul_f32 v[72:73], v[158:159], v[158:159]
	v_lshlrev_b32_e32 v156, 16, v29
	v_and_b32_e32 v157, 0xffff0000, v29
	v_add_f32_e32 v0, v30, v0
	v_add_f32_e32 v26, v26, v27
	v_pk_mul_f32 v[28:29], v[156:157], v[156:157]
	s_waitcnt vmcnt(6)
	v_lshlrev_b32_e32 v162, 16, v22
	v_and_b32_e32 v163, 0xffff0000, v22
	v_add_f32_e32 v0, v26, v0
	v_add_f32_e32 v26, v72, v73
	v_pk_mul_f32 v[74:75], v[162:163], v[162:163]
	v_lshlrev_b32_e32 v166, 16, v23
	v_and_b32_e32 v167, 0xffff0000, v23
	v_add_f32_e32 v0, v26, v0
	v_add_f32_e32 v26, v28, v29
	v_pk_mul_f32 v[22:23], v[166:167], v[166:167]
	v_lshlrev_b32_e32 v164, 16, v24
	v_and_b32_e32 v165, 0xffff0000, v24
	v_add_f32_e32 v0, v26, v0
	v_add_f32_e32 v26, v74, v75
	v_pk_mul_f32 v[76:77], v[164:165], v[164:165]
	v_lshlrev_b32_e32 v168, 16, v25
	v_and_b32_e32 v169, 0xffff0000, v25
	v_add_f32_e32 v0, v26, v0
	v_add_f32_e32 v22, v22, v23
	v_pk_mul_f32 v[24:25], v[168:169], v[168:169]
	s_waitcnt vmcnt(5)
	v_lshlrev_b32_e32 v170, 16, v18
	v_and_b32_e32 v171, 0xffff0000, v18
	v_add_f32_e32 v0, v22, v0
	v_add_f32_e32 v22, v76, v77
	v_pk_mul_f32 v[78:79], v[170:171], v[170:171]
	v_lshlrev_b32_e32 v172, 16, v19
	v_and_b32_e32 v173, 0xffff0000, v19
	v_add_f32_e32 v0, v22, v0
	v_add_f32_e32 v22, v24, v25
	v_pk_mul_f32 v[18:19], v[172:173], v[172:173]
	v_lshlrev_b32_e32 v182, 16, v20
	v_and_b32_e32 v183, 0xffff0000, v20
	v_add_f32_e32 v0, v22, v0
	v_add_f32_e32 v22, v78, v79
	v_pk_mul_f32 v[80:81], v[182:183], v[182:183]
	v_lshlrev_b32_e32 v184, 16, v21
	v_and_b32_e32 v185, 0xffff0000, v21
	v_add_f32_e32 v0, v22, v0
	v_add_f32_e32 v18, v18, v19
	v_pk_mul_f32 v[20:21], v[184:185], v[184:185]
	s_waitcnt vmcnt(4)
	v_lshlrev_b32_e32 v188, 16, v14
	v_and_b32_e32 v189, 0xffff0000, v14
	v_add_f32_e32 v0, v18, v0
	v_add_f32_e32 v18, v80, v81
	v_pk_mul_f32 v[82:83], v[188:189], v[188:189]
	v_lshlrev_b32_e32 v186, 16, v15
	v_and_b32_e32 v187, 0xffff0000, v15
	v_add_f32_e32 v0, v18, v0
	v_add_f32_e32 v18, v20, v21
	v_pk_mul_f32 v[14:15], v[186:187], v[186:187]
	v_lshlrev_b32_e32 v196, 16, v16
	v_and_b32_e32 v197, 0xffff0000, v16
	v_add_f32_e32 v0, v18, v0
	v_add_f32_e32 v18, v82, v83
	v_pk_mul_f32 v[84:85], v[196:197], v[196:197]
	v_lshlrev_b32_e32 v194, 16, v17
	v_and_b32_e32 v195, 0xffff0000, v17
	v_add_f32_e32 v0, v18, v0
	v_add_f32_e32 v14, v14, v15
	v_pk_mul_f32 v[16:17], v[194:195], v[194:195]
	s_waitcnt vmcnt(3)
	v_lshlrev_b32_e32 v202, 16, v6
	v_and_b32_e32 v203, 0xffff0000, v6
	v_add_f32_e32 v0, v14, v0
	v_add_f32_e32 v14, v84, v85
	s_waitcnt vmcnt(2)
	v_and_b32_e32 v193, 0xffff0000, v11
	v_pk_mul_f32 v[86:87], v[202:203], v[202:203]
	v_lshlrev_b32_e32 v206, 16, v7
	v_and_b32_e32 v207, 0xffff0000, v7
	v_and_b32_e32 v201, 0xffff0000, v9
	v_add_f32_e32 v0, v14, v0
	v_add_f32_e32 v14, v16, v17
	v_lshlrev_b32_e32 v192, 16, v10
	v_and_b32_e32 v215, 0xffff0000, v10
	v_mov_b32_e32 v214, v193
	v_pk_mul_f32 v[6:7], v[206:207], v[206:207]
	v_lshlrev_b32_e32 v212, 16, v8
	v_and_b32_e32 v223, 0xffff0000, v8
	v_mov_b32_e32 v222, v201
	v_add_f32_e32 v0, v14, v0
	v_add_f32_e32 v14, v86, v87
	v_lshlrev_b32_e32 v190, 16, v11
	v_mov_b32_e32 v191, v192
	v_pk_mul_f32 v[10:11], v[214:215], v[214:215]
	v_lshlrev_b32_e32 v220, 16, v9
	v_mov_b32_e32 v221, v212
	v_pk_mul_f32 v[8:9], v[222:223], v[222:223]
	v_add_f32_e32 v0, v14, v0
	v_add_f32_e32 v6, v6, v7
	v_pk_fma_f32 v[10:11], v[190:191], v[190:191], v[10:11]
	v_and_b32_e32 v191, 0xffff0000, v13
	v_pk_fma_f32 v[8:9], v[220:221], v[220:221], v[8:9]
	v_add_f32_e32 v0, v6, v0
	v_lshlrev_b32_e32 v200, 16, v12
	v_and_b32_e32 v217, 0xffff0000, v12
	v_mov_b32_e32 v216, v191
	v_add_f32_e32 v0, v9, v0
	v_lshlrev_b32_e32 v198, 16, v13
	v_mov_b32_e32 v199, v200
	v_pk_mul_f32 v[12:13], v[216:217], v[216:217]
	v_add_f32_e32 v0, v8, v0
	v_pk_fma_f32 v[12:13], v[198:199], v[198:199], v[12:13]
	s_waitcnt vmcnt(1)
	v_and_b32_e32 v199, 0xffff0000, v3
	v_add_f32_e32 v0, v11, v0
	v_lshlrev_b32_e32 v204, 16, v2
	v_and_b32_e32 v219, 0xffff0000, v2
	v_mov_b32_e32 v218, v199
	v_add_f32_e32 v0, v10, v0
	v_lshlrev_b32_e32 v208, 16, v3
	v_mov_b32_e32 v209, v204
	v_pk_mul_f32 v[2:3], v[218:219], v[218:219]
	v_and_b32_e32 v205, 0xffff0000, v5
	v_add_f32_e32 v0, v13, v0
	v_pk_fma_f32 v[2:3], v[208:209], v[208:209], v[2:3]
	v_lshlrev_b32_e32 v210, 16, v4
	v_and_b32_e32 v225, 0xffff0000, v4
	v_mov_b32_e32 v224, v205
	v_add_f32_e32 v0, v12, v0
	v_lshlrev_b32_e32 v226, 16, v5
	v_mov_b32_e32 v227, v210
	v_pk_mul_f32 v[4:5], v[224:225], v[224:225]
	v_add_f32_e32 v0, v3, v0
	v_pk_fma_f32 v[4:5], v[226:227], v[226:227], v[4:5]
	v_add_f32_e32 v0, v2, v0
	v_add_f32_e32 v0, v5, v0
	v_add_f32_e32 v209, v4, v0
	v_and_b32_e32 v0, 32, v98
	global_load_dwordx4 v[2:5], v0, s[24:25] offset:16
	global_load_dwordx4 v[14:17], v0, s[24:25]
	global_load_dwordx4 v[18:21], v0, s[24:25] offset:80
	global_load_dwordx4 v[22:25], v0, s[24:25] offset:64
	global_load_dwordx4 v[26:29], v0, s[24:25] offset:144
	global_load_dwordx4 v[30:33], v0, s[24:25] offset:128
	global_load_dwordx4 v[34:37], v0, s[24:25] offset:208
	global_load_dwordx4 v[38:41], v0, s[24:25] offset:192
	global_load_dwordx4 v[42:45], v0, s[24:25] offset:272
	global_load_dwordx4 v[46:49], v0, s[24:25] offset:256
	global_load_dwordx4 v[50:53], v0, s[24:25] offset:336
	global_load_dwordx4 v[54:57], v0, s[24:25] offset:320
	global_load_dwordx4 v[58:61], v0, s[24:25] offset:400
	global_load_dwordx4 v[62:65], v0, s[24:25] offset:384
	global_load_dwordx4 v[66:69], v0, s[24:25] offset:464
	global_load_dwordx4 v[70:73], v0, s[24:25] offset:448
	global_load_dwordx4 v[78:81], v0, s[24:25] offset:528
	global_load_dwordx4 v[86:89], v0, s[24:25] offset:512
	global_load_dwordx4 v[74:77], v0, s[24:25] offset:656
	global_load_dwordx4 v[82:85], v0, s[24:25] offset:640
	global_load_dwordx4 v[10:13], v0, s[24:25] offset:592
	global_load_dwordx4 v[90:93], v0, s[24:25] offset:576
	global_load_dwordx4 v[6:9], v0, s[24:25] offset:720
	global_load_dwordx4 v[94:97], v0, s[24:25] offset:704
	v_bfe_u32 v0, v98, 4, 2
	v_or_b32_e32 v99, s7, v0
	v_lshlrev_b32_e32 v99, 1, v99
	v_bitop3_b32 v0, s7, v98, v0 bitop3:0x36
	v_or_b32_e32 v103, v99, v102
	v_mad_i64_i32 v[100:101], s[10:11], v103, s46, v[100:101]
	v_lshlrev_b32_e32 v0, 4, v0
	v_lshl_add_u64 v[100:101], v[100:101], 0, s[86:87]
	v_and_b32_e32 v0, 0x70, v0
	v_add_u32_e32 v99, s44, v99
	v_lshl_add_u64 v[174:175], v[100:101], 0, v[0:1]
	v_or_b32_e32 v100, v99, v102
	v_ashrrev_i32_e32 v101, 31, v100
	v_lshlrev_b64 v[100:101], 15, v[100:101]
	global_load_lds_dwordx4 v[174:175], off
	v_lshl_add_u64 v[102:103], v[174:175], 0, s[94:95]
	s_add_i32 m0, s0, 0x2000
	v_lshl_add_u64 v[100:101], s[12:13], 0, v[100:101]
	global_load_lds_dwordx4 v[102:103], off
	v_lshl_add_u64 v[102:103], v[174:175], 0, s[96:97]
	s_add_i32 m0, s0, 0x4000
	v_lshl_add_u64 v[180:181], v[100:101], 0, v[0:1]
	global_load_lds_dwordx4 v[102:103], off
	s_add_i32 m0, s0, 0x6000
	v_lshl_add_u64 v[100:101], v[180:181], 0, s[92:93]
	global_load_lds_dwordx4 v[180:181], off
	s_add_i32 m0, s0, 0x8000
	s_mov_b64 s[10:11], 0x30000
	global_load_lds_dwordx4 v[100:101], off
	v_lshl_add_u64 v[100:101], v[174:175], 0, s[10:11]
	s_add_i32 m0, s0, 0xa000
	s_mov_b64 s[10:11], 0x30080
	global_load_lds_dwordx4 v[100:101], off
	v_lshl_add_u64 v[100:101], v[174:175], 0, s[10:11]
	s_add_i32 m0, s0, 0xc000
	s_mov_b64 s[10:11], 0x30100
	global_load_lds_dwordx4 v[100:101], off
	v_lshl_add_u64 v[100:101], v[174:175], 0, s[10:11]
	s_add_i32 m0, s0, 0xe000
	s_mov_b64 s[10:11], 0x200080
	global_load_lds_dwordx4 v[100:101], off
	s_add_i32 m0, s0, 0x10000
	v_lshl_add_u64 v[100:101], v[180:181], 0, s[94:95]
	global_load_lds_dwordx4 v[100:101], off
	v_lshl_add_u64 v[100:101], v[180:181], 0, s[10:11]
	s_add_i32 m0, s0, 0x12000
	ds_bpermute_b32 v211, v231, v209
	global_load_lds_dwordx4 v[100:101], off
	s_waitcnt vmcnt(5)
	s_barrier
	s_cmp_lt_i32 s43, 0
	s_cbranch_scc1 .LBB0_582
	v_lshlrev_b32_e32 v0, 3, v237
	v_lshlrev_b32_e32 v0, 2, v0
	v_and_b32_e32 v222, 63, v98
	global_load_dwordx4 v[98:101], v0, s[26:27] offset:192
	global_load_dwordx4 v[102:105], v0, s[26:27] offset:176
	global_load_dwordx4 v[106:109], v0, s[26:27] offset:240
	global_load_dwordx4 v[110:113], v0, s[26:27] offset:256
	s_waitcnt lgkmcnt(0)
	v_add_f32_e32 v0, v209, v211
	v_fmamk_f32 v0, v0, 0x3baaaaab, v232
	v_cmp_gt_f32_e32 vcc, s5, v0
	v_mul_f32_e32 v176, 0x4b800000, v0
	v_mov_b32_e32 v213, v223
	v_cndmask_b32_e32 v0, v0, v176, vcc
	v_rsq_f32_e32 v0, v0
	s_waitcnt vmcnt(0)
	v_cvt_f32_i32_e32 v223, v239
	v_mov_b32_e32 v221, v201
	v_mov_b32_e32 v227, v205
	v_mul_f32_e32 v176, 0x45800000, v0
	v_cndmask_b32_e32 v0, v0, v176, vcc
	v_mul_f32_e32 v0, 0x3dd53b94, v0
	v_mov_b32_e32 v205, v219
	v_mov_b32_e32 v201, v217
	v_pk_mul_f32 v[216:217], v[0:1], v[220:221] op_sel_hi:[0,1]
	v_mov_b32_e32 v211, v225
	v_mov_b32_e32 v209, v199
	v_mov_b32_e32 v199, v191
	v_mov_b32_e32 v191, v193
	v_mov_b32_e32 v193, v215
	v_pk_mul_f32 v[214:215], v[0:1], v[226:227] op_sel_hi:[0,1]
	s_lshl_b32 s21, s43, 2
	s_ashr_i32 s9, s9, 7
	s_mov_b32 s7, 2
	s_add_i32 s9, s9, s21
	s_add_i32 s21, s21, 4
	s_mov_b32 s28, 0
	s_movk_i32 s86, 0x80
	s_mov_b32 s33, 0
	v_mul_f32_e32 v99, v99, v223
	v_mul_f32_e32 v98, v98, v223
	v_mul_f32_e32 v109, v109, v223
	v_mul_f32_e32 v113, v113, v223
	v_cvt_f64_f32_e32 v[176:177], v113
	v_mul_f64 v[178:179], v[176:177], s[84:85]
	v_rndne_f64_e32 v[178:179], v[178:179]
	v_fma_f64 v[176:177], v[176:177], s[84:85], -v[178:179]
	v_cvt_f32_f64_e32 v113, v[176:177]
	v_mul_f32_e32 v112, v112, v223
	v_cos_f32_e32 v219, v113
	v_sin_f32_e32 v221, v113
	v_cvt_f64_f32_e32 v[112:113], v112
	v_mul_f64 v[176:177], v[112:113], s[84:85]
	v_rndne_f64_e32 v[176:177], v[176:177]
	v_fma_f64 v[112:113], v[112:113], s[84:85], -v[176:177]
	v_cvt_f32_f64_e32 v112, v[112:113]
	v_mul_f32_e32 v111, v111, v223
	v_sin_f32_e32 v220, v112
	v_cos_f32_e32 v218, v112
	v_cvt_f64_f32_e32 v[112:113], v111
	v_mul_f64 v[176:177], v[112:113], s[84:85]
	v_rndne_f64_e32 v[176:177], v[176:177]
	v_mul_f32_e32 v110, v110, v223
	v_fma_f64 v[112:113], v[112:113], s[84:85], -v[176:177]
	v_pk_mul_f32 v[178:179], v[0:1], v[210:211] op_sel_hi:[0,1]
	v_cvt_f64_f32_e32 v[210:211], v110
	v_cvt_f32_f64_e32 v176, v[112:113]
	v_pk_mul_f32 v[112:113], v[0:1], v[212:213] op_sel_hi:[0,1]
	v_mul_f64 v[212:213], v[210:211], s[84:85]
	v_rndne_f64_e32 v[212:213], v[212:213]
	v_fma_f64 v[210:211], v[210:211], s[84:85], -v[212:213]
	v_sin_f32_e32 v111, v176
	v_cos_f32_e32 v177, v176
	v_cvt_f32_f64_e32 v176, v[210:211]
	v_sin_f32_e32 v110, v176
	v_cos_f32_e32 v176, v176
	v_pk_mul_f32 v[6:7], v[6:7], v[178:179]
	v_pk_mul_f32 v[112:113], v[10:11], v[112:113]
	v_mul_f32_e32 v108, v108, v223
	v_pk_mul_f32 v[10:11], v[176:177], v[6:7]
	v_pk_mul_f32 v[6:7], v[110:111], v[6:7]
	v_pk_fma_f32 v[10:11], v[110:111], v[112:113], v[10:11]
	v_cvt_f64_f32_e32 v[110:111], v109
	v_pk_fma_f32 v[6:7], v[176:177], v[112:113], v[6:7] neg_lo:[0,0,1] neg_hi:[0,0,1]
	v_mul_f64 v[112:113], v[110:111], s[84:85]
	v_rndne_f64_e32 v[112:113], v[112:113]
	v_cvt_f64_f32_e32 v[178:179], v108
	v_fma_f64 v[110:111], v[110:111], s[84:85], -v[112:113]
	v_pk_mul_f32 v[112:113], v[0:1], v[206:207] op_sel_hi:[0,1]
	v_mul_f64 v[206:207], v[178:179], s[84:85]
	v_rndne_f64_e32 v[206:207], v[206:207]
	v_cvt_f32_f64_e32 v110, v[110:111]
	v_fma_f64 v[178:179], v[178:179], s[84:85], -v[206:207]
	v_sin_f32_e32 v109, v110
	v_cos_f32_e32 v111, v110
	v_cvt_f32_f64_e32 v110, v[178:179]
	v_sin_f32_e32 v108, v110
	v_cos_f32_e32 v110, v110
	v_pk_mul_f32 v[176:177], v[0:1], v[208:209] op_sel_hi:[0,1]
	v_pk_mul_f32 v[96:97], v[96:97], v[176:177]
	v_pk_mul_f32 v[92:93], v[92:93], v[112:113]
	v_pk_mul_f32 v[112:113], v[110:111], v[96:97]
	v_pk_mul_f32 v[96:97], v[108:109], v[96:97]
	v_pk_fma_f32 v[208:209], v[108:109], v[92:93], v[112:113]
	v_pk_fma_f32 v[206:207], v[110:111], v[92:93], v[96:97] neg_lo:[0,0,1] neg_hi:[0,0,1]
	v_mul_f32_e32 v92, v107, v223
	v_cvt_f64_f32_e32 v[92:93], v92
	v_mul_f64 v[96:97], v[92:93], s[84:85]
	v_rndne_f64_e32 v[96:97], v[96:97]
	v_fma_f64 v[92:93], v[92:93], s[84:85], -v[96:97]
	v_cvt_f32_f64_e32 v92, v[92:93]
	v_sin_f32_e32 v93, v92
	v_cos_f32_e32 v107, v92
	v_mul_f32_e32 v92, v106, v223
	v_cvt_f64_f32_e32 v[110:111], v92
	v_mul_f64 v[112:113], v[110:111], s[84:85]
	v_rndne_f64_e32 v[112:113], v[112:113]
	v_fma_f64 v[110:111], v[110:111], s[84:85], -v[112:113]
	v_cvt_f32_f64_e32 v106, v[110:111]
	v_sin_f32_e32 v92, v106
	v_cos_f32_e32 v106, v106
	v_pk_mul_f32 v[108:109], v[0:1], v[204:205] op_sel_hi:[0,1]
	v_pk_mul_f32 v[96:97], v[0:1], v[202:203] op_sel_hi:[0,1]
	v_pk_mul_f32 v[94:95], v[94:95], v[108:109]
	v_pk_mul_f32 v[90:91], v[90:91], v[96:97]
	v_pk_mul_f32 v[96:97], v[106:107], v[94:95]
	v_cvt_f64_f32_e32 v[178:179], v99
	v_pk_fma_f32 v[204:205], v[92:93], v[90:91], v[96:97]
	v_pk_mul_f32 v[92:93], v[92:93], v[94:95]
	v_mul_f32_e32 v100, v100, v223
	v_pk_fma_f32 v[202:203], v[106:107], v[90:91], v[92:93] neg_lo:[0,0,1] neg_hi:[0,0,1]
	v_mul_f32_e32 v90, v102, v223
	v_cvt_f64_f32_e32 v[90:91], v90
	v_mul_f64 v[92:93], v[90:91], s[84:85]
	v_rndne_f64_e32 v[92:93], v[92:93]
	v_fma_f64 v[90:91], v[90:91], s[84:85], -v[92:93]
	v_cvt_f32_f64_e32 v91, v[90:91]
	v_sin_f32_e32 v90, v91
	v_cos_f32_e32 v94, v91
	v_mul_f32_e32 v91, v103, v223
	v_cvt_f64_f32_e32 v[102:103], v91
	v_mul_f64 v[106:107], v[102:103], s[84:85]
	v_rndne_f64_e32 v[106:107], v[106:107]
	v_fma_f64 v[102:103], v[102:103], s[84:85], -v[106:107]
	v_cvt_f32_f64_e32 v95, v[102:103]
	v_mul_f32_e32 v102, v104, v223
	v_cvt_f64_f32_e32 v[102:103], v102
	v_mul_f64 v[106:107], v[102:103], s[84:85]
	v_rndne_f64_e32 v[106:107], v[106:107]
	v_fma_f64 v[102:103], v[102:103], s[84:85], -v[106:107]
	v_cvt_f32_f64_e32 v103, v[102:103]
	v_sin_f32_e32 v102, v103
	v_cos_f32_e32 v104, v103
	v_mul_f32_e32 v103, v105, v223
	v_cvt_f64_f32_e32 v[110:111], v103
	v_mul_f64 v[112:113], v[110:111], s[84:85]
	v_rndne_f64_e32 v[112:113], v[112:113]
	v_fma_f64 v[110:111], v[110:111], s[84:85], -v[112:113]
	v_pk_mul_f32 v[106:107], v[0:1], v[186:187] op_sel_hi:[0,1]
	v_cvt_f32_f64_e32 v105, v[110:111]
	v_cvt_f64_f32_e32 v[110:111], v98
	v_mul_f64 v[186:187], v[178:179], s[84:85]
	v_mul_f64 v[112:113], v[110:111], s[84:85]
	v_rndne_f64_e32 v[186:187], v[186:187]
	v_sin_f32_e32 v91, v95
	v_cos_f32_e32 v95, v95
	v_rndne_f64_e32 v[112:113], v[112:113]
	v_fma_f64 v[178:179], v[178:179], s[84:85], -v[186:187]
	v_mul_f32_e32 v101, v101, v223
	v_pk_mul_f32 v[108:109], v[0:1], v[190:191] op_sel_hi:[0,1]
	v_fma_f64 v[110:111], v[110:111], s[84:85], -v[112:113]
	v_cvt_f32_f64_e32 v113, v[178:179]
	v_cvt_f64_f32_e32 v[178:179], v100
	v_cvt_f64_f32_e32 v[190:191], v101
	v_pk_mul_f32 v[92:93], v[0:1], v[188:189] op_sel_hi:[0,1]
	v_pk_mul_f32 v[96:97], v[0:1], v[192:193] op_sel_hi:[0,1]
	v_sin_f32_e32 v103, v105
	v_cos_f32_e32 v105, v105
	v_mul_f64 v[186:187], v[178:179], s[84:85]
	v_mul_f64 v[192:193], v[190:191], s[84:85]
	v_cvt_f32_f64_e32 v112, v[110:111]
	v_rndne_f64_e32 v[186:187], v[186:187]
	v_rndne_f64_e32 v[192:193], v[192:193]
	v_pk_mul_f32 v[86:87], v[86:87], v[92:93]
	v_pk_mul_f32 v[92:93], v[82:83], v[96:97]
	v_sin_f32_e32 v98, v112
	v_cos_f32_e32 v112, v112
	v_sin_f32_e32 v99, v113
	v_cos_f32_e32 v113, v113
	v_fma_f64 v[178:179], v[178:179], s[84:85], -v[186:187]
	v_fma_f64 v[190:191], v[190:191], s[84:85], -v[192:193]
	v_pk_mul_f32 v[82:83], v[94:95], v[92:93]
	v_cvt_f32_f64_e32 v186, v[178:179]
	v_cvt_f32_f64_e32 v187, v[190:191]
	v_pk_fma_f32 v[82:83], v[90:91], v[86:87], v[82:83]
	v_pk_mul_f32 v[90:91], v[90:91], v[92:93]
	v_pk_mul_f32 v[84:85], v[84:85], v[108:109]
	v_pk_mul_f32 v[176:177], v[0:1], v[200:201] op_sel_hi:[0,1]
	v_sin_f32_e32 v100, v186
	v_cos_f32_e32 v186, v186
	v_sin_f32_e32 v101, v187
	v_cos_f32_e32 v187, v187
	v_pk_fma_f32 v[86:87], v[94:95], v[86:87], v[90:91] neg_lo:[0,0,1] neg_hi:[0,0,1]
	v_pk_mul_f32 v[88:89], v[88:89], v[106:107]
	v_pk_mul_f32 v[90:91], v[104:105], v[84:85]
	v_pk_mul_f32 v[84:85], v[102:103], v[84:85]
	v_pk_mul_f32 v[110:111], v[0:1], v[196:197] op_sel_hi:[0,1]
	v_pk_fma_f32 v[84:85], v[104:105], v[88:89], v[84:85] neg_lo:[0,0,1] neg_hi:[0,0,1]
	v_pk_mul_f32 v[74:75], v[74:75], v[176:177]
	v_pk_mul_f32 v[188:189], v[0:1], v[198:199] op_sel_hi:[0,1]
	v_cvt_pk_bf16_f32 v86, v86, v87
	v_cvt_pk_bf16_f32 v87, v84, v85
	v_pk_mul_f32 v[78:79], v[78:79], v[110:111]
	v_pk_mul_f32 v[84:85], v[112:113], v[74:75]
	v_pk_mul_f32 v[74:75], v[98:99], v[74:75]
	v_pk_mul_f32 v[178:179], v[0:1], v[194:195] op_sel_hi:[0,1]
	v_pk_fma_f32 v[74:75], v[112:113], v[78:79], v[74:75] neg_lo:[0,0,1] neg_hi:[0,0,1]
	v_pk_mul_f32 v[76:77], v[76:77], v[188:189]
	v_pk_fma_f32 v[90:91], v[102:103], v[88:89], v[90:91]
	v_pk_fma_f32 v[84:85], v[98:99], v[78:79], v[84:85]
	v_cvt_pk_bf16_f32 v88, v74, v75
	v_pk_mul_f32 v[74:75], v[80:81], v[178:179]
	v_pk_mul_f32 v[78:79], v[186:187], v[76:77]
	v_pk_mul_f32 v[76:77], v[100:101], v[76:77]
	v_pk_fma_f32 v[78:79], v[100:101], v[74:75], v[78:79]
	v_pk_fma_f32 v[74:75], v[186:187], v[74:75], v[76:77] neg_lo:[0,0,1] neg_hi:[0,0,1]
	v_cvt_pk_bf16_f32 v82, v82, v83
	v_cvt_pk_bf16_f32 v89, v74, v75
	v_pk_mul_f32 v[74:75], v[0:1], v[170:171] op_sel_hi:[0,1]
	v_pk_mul_f32 v[70:71], v[70:71], v[74:75]
	v_cvt_pk_bf16_f32 v83, v90, v91
	v_cvt_pk_bf16_f32 v90, v70, v71
	v_pk_mul_f32 v[70:71], v[0:1], v[172:173] op_sel_hi:[0,1]
	v_pk_mul_f32 v[70:71], v[72:73], v[70:71]
	v_cvt_pk_bf16_f32 v84, v84, v85
	v_cvt_pk_bf16_f32 v91, v70, v71
	v_pk_mul_f32 v[70:71], v[0:1], v[182:183] op_sel_hi:[0,1]
	v_pk_mul_f32 v[66:67], v[66:67], v[70:71]
	v_cvt_pk_bf16_f32 v85, v78, v79
	v_cvt_pk_bf16_f32 v92, v66, v67
	v_pk_mul_f32 v[66:67], v[0:1], v[184:185] op_sel_hi:[0,1]
	v_pk_mul_f32 v[66:67], v[68:69], v[66:67]
	s_nop 0
	v_cvt_pk_bf16_f32 v93, v66, v67
	v_pk_mul_f32 v[66:67], v[0:1], v[162:163] op_sel_hi:[0,1]
	v_pk_mul_f32 v[62:63], v[62:63], v[66:67]
	s_nop 0
	v_cvt_pk_bf16_f32 v94, v62, v63
	v_pk_mul_f32 v[62:63], v[0:1], v[166:167] op_sel_hi:[0,1]
	v_pk_mul_f32 v[62:63], v[64:65], v[62:63]
	s_nop 0
	v_cvt_pk_bf16_f32 v95, v62, v63
	v_pk_mul_f32 v[62:63], v[0:1], v[164:165] op_sel_hi:[0,1]
	v_pk_mul_f32 v[58:59], v[58:59], v[62:63]
	s_nop 0
	v_cvt_pk_bf16_f32 v96, v58, v59
	v_pk_mul_f32 v[58:59], v[0:1], v[168:169] op_sel_hi:[0,1]
	v_pk_mul_f32 v[58:59], v[60:61], v[58:59]
	s_nop 0
	v_cvt_pk_bf16_f32 v97, v58, v59
	v_pk_mul_f32 v[58:59], v[0:1], v[154:155] op_sel_hi:[0,1]
	v_pk_mul_f32 v[54:55], v[54:55], v[58:59]
	s_nop 0
	v_cvt_pk_bf16_f32 v98, v54, v55
	v_pk_mul_f32 v[54:55], v[0:1], v[160:161] op_sel_hi:[0,1]
	v_pk_mul_f32 v[54:55], v[56:57], v[54:55]
	s_nop 0
	v_cvt_pk_bf16_f32 v99, v54, v55
	v_pk_mul_f32 v[54:55], v[0:1], v[158:159] op_sel_hi:[0,1]
	v_pk_mul_f32 v[50:51], v[50:51], v[54:55]
	s_nop 0
	v_cvt_pk_bf16_f32 v100, v50, v51
	v_pk_mul_f32 v[50:51], v[0:1], v[156:157] op_sel_hi:[0,1]
	v_pk_mul_f32 v[50:51], v[52:53], v[50:51]
	s_nop 0
	v_cvt_pk_bf16_f32 v101, v50, v51
	v_pk_mul_f32 v[50:51], v[0:1], v[146:147] op_sel_hi:[0,1]
	v_pk_mul_f32 v[46:47], v[46:47], v[50:51]
	v_mov_b32_e32 v50, 0
	v_cvt_pk_bf16_f32 v102, v46, v47
	v_pk_mul_f32 v[46:47], v[0:1], v[148:149] op_sel_hi:[0,1]
	v_pk_mul_f32 v[46:47], v[48:49], v[46:47]
	s_nop 0
	v_cvt_pk_bf16_f32 v103, v46, v47
	v_pk_mul_f32 v[46:47], v[0:1], v[150:151] op_sel_hi:[0,1]
	v_pk_mul_f32 v[42:43], v[42:43], v[46:47]
	s_nop 0
	v_cvt_pk_bf16_f32 v104, v42, v43
	v_pk_mul_f32 v[42:43], v[0:1], v[152:153] op_sel_hi:[0,1]
	v_pk_mul_f32 v[42:43], v[44:45], v[42:43]
	s_nop 0
	v_cvt_pk_bf16_f32 v105, v42, v43
	v_pk_mul_f32 v[42:43], v[0:1], v[138:139] op_sel_hi:[0,1]
	v_pk_mul_f32 v[38:39], v[38:39], v[42:43]
	s_nop 0
	v_cvt_pk_bf16_f32 v106, v38, v39
	v_pk_mul_f32 v[38:39], v[0:1], v[140:141] op_sel_hi:[0,1]
	v_pk_mul_f32 v[38:39], v[40:41], v[38:39]
	s_nop 0
	v_cvt_pk_bf16_f32 v107, v38, v39
	v_pk_mul_f32 v[38:39], v[0:1], v[142:143] op_sel_hi:[0,1]
	v_pk_mul_f32 v[34:35], v[34:35], v[38:39]
	s_nop 0
	v_cvt_pk_bf16_f32 v108, v34, v35
	v_pk_mul_f32 v[34:35], v[0:1], v[144:145] op_sel_hi:[0,1]
	v_pk_mul_f32 v[34:35], v[36:37], v[34:35]
	s_nop 0
	v_cvt_pk_bf16_f32 v109, v34, v35
	v_pk_mul_f32 v[34:35], v[0:1], v[130:131] op_sel_hi:[0,1]
	v_pk_mul_f32 v[30:31], v[30:31], v[34:35]
	v_mov_b32_e32 v34, 0
	v_cvt_pk_bf16_f32 v110, v30, v31
	v_pk_mul_f32 v[30:31], v[0:1], v[132:133] op_sel_hi:[0,1]
	v_pk_mul_f32 v[30:31], v[32:33], v[30:31]
	s_nop 0
	v_cvt_pk_bf16_f32 v111, v30, v31
	v_pk_mul_f32 v[30:31], v[0:1], v[134:135] op_sel_hi:[0,1]
	v_pk_mul_f32 v[26:27], v[26:27], v[30:31]
	s_nop 0
	v_cvt_pk_bf16_f32 v112, v26, v27
	v_pk_mul_f32 v[26:27], v[0:1], v[136:137] op_sel_hi:[0,1]
	v_pk_mul_f32 v[26:27], v[28:29], v[26:27]
	s_nop 0
	v_cvt_pk_bf16_f32 v113, v26, v27
	v_pk_mul_f32 v[26:27], v[0:1], v[114:115] op_sel_hi:[0,1]
	v_pk_mul_f32 v[22:23], v[22:23], v[26:27]
	s_nop 0
	v_cvt_pk_bf16_f32 v114, v22, v23
	v_pk_mul_f32 v[22:23], v[0:1], v[116:117] op_sel_hi:[0,1]
	v_pk_mul_f32 v[22:23], v[24:25], v[22:23]
	s_nop 0
	v_cvt_pk_bf16_f32 v115, v22, v23
	v_pk_mul_f32 v[22:23], v[0:1], v[126:127] op_sel_hi:[0,1]
	v_pk_mul_f32 v[18:19], v[18:19], v[22:23]
	v_cvt_pk_bf16_f32 v126, v202, v203
	v_cvt_pk_bf16_f32 v116, v18, v19
	v_pk_mul_f32 v[18:19], v[0:1], v[128:129] op_sel_hi:[0,1]
	v_pk_mul_f32 v[18:19], v[20:21], v[18:19]
	v_cvt_pk_bf16_f32 v128, v6, v7
	v_cvt_pk_bf16_f32 v117, v18, v19
	v_pk_mul_f32 v[18:19], v[0:1], v[118:119] op_sel_hi:[0,1]
	v_pk_mul_f32 v[14:15], v[14:15], v[18:19]
	v_cvt_pk_bf16_f32 v127, v206, v207
	v_cvt_pk_bf16_f32 v118, v14, v15
	v_pk_mul_f32 v[14:15], v[0:1], v[120:121] op_sel_hi:[0,1]
	v_pk_mul_f32 v[14:15], v[16:17], v[14:15]
	v_mov_b32_e32 v18, 0
	v_cvt_pk_bf16_f32 v119, v14, v15
	v_pk_mul_f32 v[14:15], v[0:1], v[122:123] op_sel_hi:[0,1]
	v_pk_mul_f32 v[2:3], v[2:3], v[14:15]
	v_cvt_pk_bf16_f32 v122, v204, v205
	v_cvt_pk_bf16_f32 v120, v2, v3
	v_pk_mul_f32 v[2:3], v[0:1], v[124:125] op_sel_hi:[0,1]
	v_pk_mul_f32 v[2:3], v[4:5], v[2:3]
	v_pk_mul_f32 v[4:5], v[8:9], v[214:215]
	v_cvt_pk_bf16_f32 v121, v2, v3
	v_pk_mul_f32 v[2:3], v[12:13], v[216:217]
	v_pk_mul_f32 v[6:7], v[218:219], v[4:5]
	v_pk_mul_f32 v[4:5], v[220:221], v[4:5]
	v_pk_fma_f32 v[6:7], v[220:221], v[2:3], v[6:7]
	v_pk_fma_f32 v[2:3], v[218:219], v[2:3], v[4:5] neg_lo:[0,0,1] neg_hi:[0,0,1]
	v_mov_b32_e32 v0, 0
	v_cvt_pk_bf16_f32 v123, v208, v209
	v_cvt_pk_bf16_f32 v124, v10, v11
	v_cvt_pk_bf16_f32 v125, v6, v7
	v_cvt_pk_bf16_f32 v129, v2, v3
	v_mov_b32_e32 v2, 0
	v_mov_b32_e32 v3, v0
	v_mov_b32_e32 v4, v0
	v_mov_b32_e32 v5, v0
	v_mov_b32_e32 v6, v0
	v_mov_b32_e32 v7, v0
	v_mov_b32_e32 v8, v0
	v_mov_b32_e32 v9, v0
	v_mov_b32_e32 v10, v0
	v_mov_b32_e32 v11, v0
	v_mov_b32_e32 v12, v0
	v_mov_b32_e32 v13, v0
	v_mov_b32_e32 v14, v0
	v_mov_b32_e32 v15, v0
	v_mov_b32_e32 v16, v0
	v_mov_b32_e32 v17, v0
	v_mov_b32_e32 v19, v0
	v_mov_b32_e32 v20, v0
	v_mov_b32_e32 v21, v0
	v_mov_b32_e32 v22, v0
	v_mov_b32_e32 v23, v0
	v_mov_b32_e32 v24, v0
	v_mov_b32_e32 v25, v0
	v_mov_b32_e32 v26, v0
	v_mov_b32_e32 v27, v0
	v_mov_b32_e32 v28, v0
	v_mov_b32_e32 v29, v0
	v_mov_b32_e32 v30, v0
	v_mov_b32_e32 v31, v0
	v_mov_b32_e32 v32, v0
	v_mov_b32_e32 v33, v0
	v_mov_b32_e32 v35, v0
	v_mov_b32_e32 v36, v0
	v_mov_b32_e32 v37, v0
	v_mov_b32_e32 v38, v0
	v_mov_b32_e32 v39, v0
	v_mov_b32_e32 v40, v0
	v_mov_b32_e32 v41, v0
	v_mov_b32_e32 v42, v0
	v_mov_b32_e32 v43, v0
	v_mov_b32_e32 v44, v0
	v_mov_b32_e32 v45, v0
	v_mov_b32_e32 v46, v0
	v_mov_b32_e32 v47, v0
	v_mov_b32_e32 v48, v0
	v_mov_b32_e32 v49, v0
	v_mov_b32_e32 v51, v0
	v_mov_b32_e32 v52, v0
	v_mov_b32_e32 v53, v0
	v_mov_b32_e32 v54, v0
	v_mov_b32_e32 v55, v0
	v_mov_b32_e32 v56, v0
	v_mov_b32_e32 v57, v0
	v_mov_b32_e32 v58, v0
	v_mov_b32_e32 v59, v0
	v_mov_b32_e32 v60, v0
	v_mov_b32_e32 v61, v0
	v_mov_b32_e32 v62, v0
	v_mov_b32_e32 v63, v0
	v_mov_b32_e32 v64, v0
	v_mov_b32_e32 v65, v0
	v_mov_b32_e32 v208, v222
	v_lshlrev_b32_e32 v211, 3, v208
	v_lshrrev_b32_e32 v209, 1, v208
	v_lshlrev_b32_e32 v210, 7, v208
	v_and_b32_e32 v211, 8, v211
	v_ashrrev_i32_e32 v208, 5, v208
	v_add_u32_e32 v208, v211, v208
	v_and_b32_e32 v210, 0xf00, v210
	v_bitop3_b32 v211, v208, v209, 7 bitop3:0x78
	v_add_u32_e32 v212, 2, v208
	v_add_u32_e32 v213, 4, v208
	v_add_u32_e32 v208, 6, v208
	v_bitop3_b32 v212, v212, v209, 7 bitop3:0x78
	v_bitop3_b32 v213, v213, v209, 7 bitop3:0x78
	v_bitop3_b32 v208, v208, v209, 7 bitop3:0x78
	v_lshl_add_u32 v218, v211, 4, v210
	v_lshl_add_u32 v219, v212, 4, v210
	v_lshl_add_u32 v209, v213, 4, v210
	v_lshl_add_u32 v208, v208, 4, v210
	s_branch .LBB0_574

.LBB0_615:
	s_waitcnt vmcnt(0)
	v_readlane_b32 s0, v255, 16
	v_readlane_b32 s1, v255, 17
	s_and_b64 vcc, exec, s[0:1]
	s_cbranch_vccnz .LBB0_618
	s_load_dwordx2 s[0:1], s[26:27], 0x60
	v_readlane_b32 s6, v255, 10
	v_readlane_b32 s7, v255, 11
	s_lshl_b64 s[6:7], s[6:7], 2
	s_waitcnt lgkmcnt(0)
	s_add_u32 s6, s0, s6
	s_addc_u32 s7, s1, s7
	s_add_u32 s8, s18, 0x9f00000
	s_addc_u32 s9, s19, 0
	s_add_u32 s10, s18, 0x19f00000
	s_addc_u32 s11, s19, 0
	s_mov_b32 s0, s2
